# F1 merged-output and E1 epilogue stores widened to dwordx4 via permlane16_swap (on top of gbuf layout + H epilogue)
# speedup vs baseline: 1.0276x; 1.0108x over previous
.LBB0_159:
	v_and_b32_e32 v10, 16, v204
	v_lshrrev_b32_e32 v11, 1, v10
	v_add_u32_e32 v10, v10, v11
	v_mov_b32_e32 v11, v189
	v_lshl_add_u64 v[10:11], v[66:67], 0, v[10:11]
	v_readlane_b32 s2, v254, 32
	v_lshlrev_b64 v[0:1], 11, v[76:77]
	v_readlane_b32 s3, v254, 33
	v_lshl_add_u64 v[0:1], s[2:3], 0, v[0:1]
	v_lshl_add_u64 v[0:1], v[0:1], 0, v[10:11]
	v_cvt_pk_bf16_f32 v2, v142, v143
	v_cvt_pk_bf16_f32 v3, v144, v145
	v_cvt_pk_bf16_f32 v4, v138, v139
	v_cvt_pk_bf16_f32 v5, v140, v141
	s_nop 1
	v_permlane16_swap_b32 v2, v4
	v_permlane16_swap_b32 v3, v5
	global_store_dwordx4 v[0:1], v[2:5], off
	s_nop 1
	v_cvt_pk_bf16_f32 v6, v134, v135
	v_cvt_pk_bf16_f32 v7, v136, v137
	v_cvt_pk_bf16_f32 v8, v130, v131
	v_cvt_pk_bf16_f32 v9, v132, v133
	s_nop 1
	v_permlane16_swap_b32 v6, v8
	v_permlane16_swap_b32 v7, v9
	global_store_dwordx4 v[0:1], v[6:9], off offset:64
	s_nop 1
	v_lshlrev_b64 v[0:1], 11, v[70:71]
	v_lshl_add_u64 v[0:1], s[2:3], 0, v[0:1]
	v_lshl_add_u64 v[0:1], v[0:1], 0, v[10:11]
	v_cvt_pk_bf16_f32 v2, v122, v123
	v_cvt_pk_bf16_f32 v3, v124, v125
	v_cvt_pk_bf16_f32 v4, v98, v99
	v_cvt_pk_bf16_f32 v5, v102, v103
	s_nop 1
	v_permlane16_swap_b32 v2, v4
	v_permlane16_swap_b32 v3, v5
	global_store_dwordx4 v[0:1], v[2:5], off
	s_nop 1
	v_cvt_pk_bf16_f32 v6, v78, v79
	v_cvt_pk_bf16_f32 v7, v80, v81
	v_cvt_pk_bf16_f32 v8, v72, v73
	v_cvt_pk_bf16_f32 v9, v74, v75
	s_nop 1
	v_permlane16_swap_b32 v6, v8
	v_permlane16_swap_b32 v7, v9
	global_store_dwordx4 v[0:1], v[6:9], off offset:64
	s_nop 1
	v_lshlrev_b64 v[0:1], 11, v[68:69]
	v_lshl_add_u64 v[0:1], s[2:3], 0, v[0:1]
	v_lshl_add_u64 v[0:1], v[0:1], 0, v[10:11]
	v_cvt_pk_bf16_f32 v2, v118, v119
	v_cvt_pk_bf16_f32 v3, v120, v121
	v_cvt_pk_bf16_f32 v4, v110, v111
	v_cvt_pk_bf16_f32 v5, v116, v117
	s_nop 1
	v_permlane16_swap_b32 v2, v4
	v_permlane16_swap_b32 v3, v5
	global_store_dwordx4 v[0:1], v[2:5], off
	s_nop 1
	v_cvt_pk_bf16_f32 v6, v106, v107
	v_cvt_pk_bf16_f32 v7, v112, v113
	v_cvt_pk_bf16_f32 v8, v104, v105
	v_cvt_pk_bf16_f32 v9, v108, v109
	s_nop 1
	v_permlane16_swap_b32 v6, v8
	v_permlane16_swap_b32 v7, v9
	global_store_dwordx4 v[0:1], v[6:9], off offset:64
	s_nop 1
	v_lshlrev_b64 v[0:1], 11, v[64:65]
	v_lshl_add_u64 v[0:1], s[2:3], 0, v[0:1]
	v_lshl_add_u64 v[0:1], v[0:1], 0, v[10:11]
	v_cvt_pk_bf16_f32 v2, v96, v97
	v_cvt_pk_bf16_f32 v3, v100, v101
	v_cvt_pk_bf16_f32 v4, v88, v89
	v_cvt_pk_bf16_f32 v5, v92, v93
	s_nop 1
	v_permlane16_swap_b32 v2, v4
	v_permlane16_swap_b32 v3, v5
	global_store_dwordx4 v[0:1], v[2:5], off
	s_nop 1
	s_add_i32 s8, s8, s96
	s_cmpk_gt_i32 s8, 0x3ff
	v_cvt_pk_bf16_f32 v6, v84, v85
	v_cvt_pk_bf16_f32 v7, v90, v91
	v_cvt_pk_bf16_f32 v8, v82, v83
	v_cvt_pk_bf16_f32 v9, v86, v87
	s_nop 1
	v_permlane16_swap_b32 v6, v8
	v_permlane16_swap_b32 v7, v9
	global_store_dwordx4 v[0:1], v[6:9], off offset:64
	s_nop 1
	s_cbranch_scc1 .LBB0_172

.LBB0_209:
	s_ashr_i32 s2, s5, 9
	s_ashr_i32 s3, s2, 31
	s_bfe_u32 s6, s5, 0x20007
	s_lshl_b64 s[8:9], s[2:3], 24
	s_add_u32 s0, s18, s8
	s_addc_u32 s3, s19, s9
	s_lshl_b32 s7, s6, 9
	v_mov_b32_e32 v12, v204
	s_add_u32 s8, s0, s7
	s_addc_u32 s9, s3, 0
	v_readfirstlane_b32 s13, v12
	s_ashr_i32 s0, s13, 6
	s_and_b32 s14, s0, 1
	s_lshl_b32 s10, s0, 3
	v_bfe_u32 v0, v12, 3, 3
	v_or_b32_e32 v8, s10, v0
	v_and_b32_e32 v0, 7, v12
	s_lshl_b32 s7, s14, 2
	v_bfe_u32 v13, v12, 4, 2
	v_bitop3_b32 v2, s7, v0, v13 bitop3:0x36
	s_lshr_b32 s7, s5, 1
	v_lshlrev_b32_e32 v0, 6, v8
	s_and_b32 s7, s7, 62
	v_and_b32_e32 v0, 0x1fc0, v0
	v_lshlrev_b32_e32 v188, 4, v2
	v_add_u32_e32 v2, 64, v8
	s_ashr_i32 s11, s13, 10
	v_or_b32_e32 v4, s7, v0
	v_ashrrev_i32_e32 v3, 7, v2
	v_lshlrev_b32_e32 v2, 6, v2
	v_add_u32_e32 v6, 0xc0, v8
	v_add_u32_e32 v0, s11, v4
	v_and_b32_e32 v2, 0x1fc0, v2
	s_addk_i32 s10, 0x80
	v_ashrrev_i32_e32 v7, 7, v6
	v_lshlrev_b32_e32 v6, 6, v6
	v_ashrrev_i32_e32 v1, 31, v0
	v_add3_u32 v2, v3, s7, v2
	s_ashr_i32 s10, s10, 7
	v_and_b32_e32 v6, 0x1fc0, v6
	v_lshlrev_b64 v[0:1], 11, v[0:1]
	v_ashrrev_i32_e32 v3, 31, v2
	v_add_u32_e32 v4, s10, v4
	v_add3_u32 v6, v7, s7, v6
	s_lshl_b32 s0, s0, 10
	s_and_b32 s3, s4, 0x180
	v_lshl_add_u64 v[0:1], s[8:9], 0, v[0:1]
	v_lshlrev_b64 v[2:3], 11, v[2:3]
	v_ashrrev_i32_e32 v5, 31, v4
	v_ashrrev_i32_e32 v7, 31, v6
	s_add_i32 s12, s0, 0
	v_lshl_add_u64 v[0:1], v[0:1], 0, v[188:189]
	v_lshl_add_u64 v[2:3], s[8:9], 0, v[2:3]
	v_lshlrev_b64 v[4:5], 11, v[4:5]
	v_lshlrev_b64 v[6:7], 11, v[6:7]
	v_add_u32_e32 v8, s3, v8
	s_mov_b32 m0, s12
	s_add_i32 s0, s12, 0x2000
	v_lshl_add_u64 v[2:3], v[2:3], 0, v[188:189]
	v_lshl_add_u64 v[4:5], s[8:9], 0, v[4:5]
	v_lshl_add_u64 v[6:7], s[8:9], 0, v[6:7]
	v_ashrrev_i32_e32 v9, 31, v8
	global_load_lds_dwordx4 v[0:1], off
	s_mov_b32 m0, s0
	s_add_i32 s8, s12, 0x4000
	v_lshl_add_u64 v[4:5], v[4:5], 0, v[188:189]
	v_lshlrev_b64 v[8:9], 9, v[8:9]
	global_load_lds_dwordx4 v[2:3], off
	s_mov_b32 m0, s8
	s_add_i32 s9, s12, 0x6000
	v_lshl_add_u64 v[6:7], v[6:7], 0, v[188:189]
	v_lshl_add_u64 v[8:9], s[16:17], 0, v[8:9]
	global_load_lds_dwordx4 v[4:5], off
	s_mov_b32 m0, s9
	s_add_i32 s10, s12, 0x8000
	v_lshl_add_u64 v[8:9], v[8:9], 0, v[188:189]
	global_load_lds_dwordx4 v[6:7], off
	s_mov_b32 m0, s10
	s_add_i32 s11, s12, 0xa000
	v_lshl_add_u64 v[10:11], v[8:9], 0, s[20:21]
	global_load_lds_dwordx4 v[8:9], off
	s_mov_b32 m0, s11
	s_lshr_b32 s13, s13, 1
	global_load_lds_dwordx4 v[10:11], off
	v_lshl_add_u64 v[10:11], v[0:1], 0, s[92:93]
	s_add_i32 m0, s12, 0xc000
	s_and_b32 s13, s13, 0x1ffffc0
	global_load_lds_dwordx4 v[10:11], off
	v_lshl_add_u64 v[10:11], v[2:3], 0, s[92:93]
	s_add_i32 m0, s12, 0xe000
	s_nop 0
	global_load_lds_dwordx4 v[10:11], off
	v_lshl_add_u64 v[10:11], v[4:5], 0, s[92:93]
	s_add_i32 m0, s12, 0x10000
	s_nop 0
	global_load_lds_dwordx4 v[10:11], off
	v_lshl_add_u64 v[10:11], v[6:7], 0, s[92:93]
	s_add_i32 m0, s12, 0x12000
	s_nop 0
	global_load_lds_dwordx4 v[10:11], off
	v_lshl_add_u64 v[10:11], v[8:9], 0, s[92:93]
	s_add_i32 m0, s12, 0x14000
	s_nop 0
	global_load_lds_dwordx4 v[10:11], off
	v_lshl_add_u64 v[10:11], v[8:9], 0, s[22:23]
	s_add_i32 m0, s12, 0x16000
	s_nop 0
	global_load_lds_dwordx4 v[10:11], off
	v_bfe_u32 v11, v12, 1, 3
	v_and_b32_e32 v10, 15, v12
	v_xor_b32_e32 v11, v13, v11
	s_waitcnt vmcnt(6)
	v_lshlrev_b32_e32 v130, 4, v11
	v_or_b32_e32 v11, s13, v10
	v_lshlrev_b32_e32 v10, 7, v10
	s_waitcnt lgkmcnt(0)
	s_barrier
	v_lshlrev_b32_e32 v131, 7, v11
	v_lshl_or_b32 v26, s14, 13, v10
	v_lshl_add_u64 v[10:11], v[0:1], 0, s[24:25]
	s_add_i32 m0, s12, 0x18000
	v_or_b32_e32 v132, 0x8000, v26
	global_load_lds_dwordx4 v[10:11], off
	v_lshl_add_u64 v[10:11], v[2:3], 0, s[24:25]
	s_add_i32 m0, s12, 0x1a000
	v_xor_b32_e32 v133, 64, v130
	global_load_lds_dwordx4 v[10:11], off
	v_lshl_add_u64 v[10:11], v[4:5], 0, s[24:25]
	s_add_i32 m0, s12, 0x1c000
	s_nop 0
	global_load_lds_dwordx4 v[10:11], off
	v_lshl_add_u64 v[10:11], v[6:7], 0, s[24:25]
	s_add_i32 m0, s12, 0x1e000
	s_nop 0
	global_load_lds_dwordx4 v[10:11], off
	v_lshl_add_u64 v[10:11], v[8:9], 0, s[24:25]
	s_add_i32 m0, s12, 0x20000
	s_nop 0
	global_load_lds_dwordx4 v[10:11], off
	v_lshl_add_u64 v[10:11], v[8:9], 0, s[26:27]
	s_add_i32 m0, s12, 0x22000
	s_nop 0
	global_load_lds_dwordx4 v[10:11], off
	v_add_u32_e32 v42, 0, v131
	v_add_u32_e32 v43, 0, v26
	v_add_u32_e32 v134, v42, v130
	v_add_u32_e32 v135, v43, v130
	v_add_u32_e32 v136, v42, v133
	ds_read_b128 v[10:13], v134
	ds_read_b128 v[14:17], v134 offset:2048
	ds_read_b128 v[18:21], v134 offset:4096
	ds_read_b128 v[22:25], v134 offset:6144
	ds_read_b128 v[26:29], v135 offset:32768
	ds_read_b128 v[30:33], v135 offset:34816
	ds_read_b128 v[34:37], v135 offset:36864
	ds_read_b128 v[38:41], v135 offset:38912
	v_add_u32_e32 v137, v43, v133
	ds_read_b128 v[42:45], v136
	ds_read_b128 v[46:49], v136 offset:2048
	ds_read_b128 v[50:53], v136 offset:4096
	ds_read_b128 v[54:57], v136 offset:6144
	ds_read_b128 v[58:61], v137 offset:32768
	ds_read_b128 v[62:65], v137 offset:34816
	ds_read_b128 v[66:69], v137 offset:36864
	ds_read_b128 v[70:73], v137 offset:38912
	s_waitcnt lgkmcnt(0)
	v_mfma_f32_16x16x32_bf16 v[74:77], v[10:13], v[26:29], 0
	v_mfma_f32_16x16x32_bf16 v[78:81], v[10:13], v[30:33], 0
	v_mfma_f32_16x16x32_bf16 v[82:85], v[10:13], v[34:37], 0
	v_mfma_f32_16x16x32_bf16 v[10:13], v[10:13], v[38:41], 0
	v_mfma_f32_16x16x32_bf16 v[86:89], v[14:17], v[26:29], 0
	v_mfma_f32_16x16x32_bf16 v[90:93], v[14:17], v[30:33], 0
	v_mfma_f32_16x16x32_bf16 v[94:97], v[14:17], v[34:37], 0
	v_mfma_f32_16x16x32_bf16 v[14:17], v[14:17], v[38:41], 0
	v_mfma_f32_16x16x32_bf16 v[98:101], v[18:21], v[26:29], 0
	v_mfma_f32_16x16x32_bf16 v[102:105], v[18:21], v[30:33], 0
	v_mfma_f32_16x16x32_bf16 v[106:109], v[18:21], v[34:37], 0
	v_mfma_f32_16x16x32_bf16 v[18:21], v[18:21], v[38:41], 0
	v_mfma_f32_16x16x32_bf16 v[26:29], v[22:25], v[26:29], 0
	v_mfma_f32_16x16x32_bf16 v[30:33], v[22:25], v[30:33], 0
	v_mfma_f32_16x16x32_bf16 v[34:37], v[22:25], v[34:37], 0
	v_mfma_f32_16x16x32_bf16 v[22:25], v[22:25], v[38:41], 0
	v_mfma_f32_16x16x32_bf16 v[38:41], v[42:45], v[58:61], v[74:77]
	v_mfma_f32_16x16x32_bf16 v[74:77], v[42:45], v[62:65], v[78:81]
	v_mfma_f32_16x16x32_bf16 v[78:81], v[42:45], v[66:69], v[82:85]
	v_mfma_f32_16x16x32_bf16 v[10:13], v[42:45], v[70:73], v[10:13]
	v_mfma_f32_16x16x32_bf16 v[42:45], v[46:49], v[58:61], v[86:89]
	v_mfma_f32_16x16x32_bf16 v[82:85], v[46:49], v[62:65], v[90:93]
	v_mfma_f32_16x16x32_bf16 v[86:89], v[46:49], v[66:69], v[94:97]
	v_mfma_f32_16x16x32_bf16 v[14:17], v[46:49], v[70:73], v[14:17]
	v_mfma_f32_16x16x32_bf16 v[46:49], v[50:53], v[58:61], v[98:101]
	v_mfma_f32_16x16x32_bf16 v[90:93], v[50:53], v[62:65], v[102:105]
	v_mfma_f32_16x16x32_bf16 v[94:97], v[50:53], v[66:69], v[106:109]
	v_mfma_f32_16x16x32_bf16 v[18:21], v[50:53], v[70:73], v[18:21]
	v_mfma_f32_16x16x32_bf16 v[26:29], v[54:57], v[58:61], v[26:29]
	v_mfma_f32_16x16x32_bf16 v[30:33], v[54:57], v[62:65], v[30:33]
	v_mfma_f32_16x16x32_bf16 v[34:37], v[54:57], v[66:69], v[34:37]
	v_mfma_f32_16x16x32_bf16 v[22:25], v[54:57], v[70:73], v[22:25]
	s_waitcnt vmcnt(6)
	s_mov_b32 m0, s12
	s_waitcnt lgkmcnt(0)
	s_barrier
	v_lshl_add_u64 v[0:1], v[0:1], 0, s[34:35]
	global_load_lds_dwordx4 v[0:1], off
	v_lshl_add_u64 v[0:1], v[2:3], 0, s[34:35]
	s_mov_b32 m0, s0
	s_nop 0
	global_load_lds_dwordx4 v[0:1], off
	v_lshl_add_u64 v[0:1], v[4:5], 0, s[34:35]
	s_mov_b32 m0, s8
	s_nop 0
	global_load_lds_dwordx4 v[0:1], off
	v_lshl_add_u64 v[0:1], v[6:7], 0, s[34:35]
	s_mov_b32 m0, s9
	s_nop 0
	global_load_lds_dwordx4 v[0:1], off
	v_lshl_add_u64 v[0:1], v[8:9], 0, s[34:35]
	s_mov_b32 m0, s10
	s_nop 0
	global_load_lds_dwordx4 v[0:1], off
	v_lshl_add_u64 v[0:1], v[8:9], 0, s[36:37]
	s_mov_b32 m0, s11
	s_nop 0
	global_load_lds_dwordx4 v[0:1], off
	s_add_i32 s0, 0, 0xc000
	v_add3_u32 v8, s0, v130, v132
	ds_read_b128 v[0:3], v134 offset:49152
	ds_read_b128 v[4:7], v134 offset:51200
	ds_read_b128 v[50:53], v134 offset:53248
	ds_read_b128 v[54:57], v134 offset:55296
	ds_read_b128 v[58:61], v8
	ds_read_b128 v[62:65], v8 offset:2048
	ds_read_b128 v[66:69], v8 offset:4096
	ds_read_b128 v[70:73], v8 offset:6144
	v_add3_u32 v8, s0, v133, v132
	ds_read_b128 v[98:101], v136 offset:49152
	ds_read_b128 v[102:105], v136 offset:51200
	ds_read_b128 v[106:109], v136 offset:53248
	ds_read_b128 v[110:113], v136 offset:55296
	ds_read_b128 v[114:117], v8
	ds_read_b128 v[118:121], v8 offset:2048
	ds_read_b128 v[122:125], v8 offset:4096
	ds_read_b128 v[126:129], v8 offset:6144
	s_waitcnt lgkmcnt(0)
	v_mfma_f32_16x16x32_bf16 v[38:41], v[0:3], v[58:61], v[38:41]
	v_mfma_f32_16x16x32_bf16 v[74:77], v[0:3], v[62:65], v[74:77]
	v_mfma_f32_16x16x32_bf16 v[78:81], v[0:3], v[66:69], v[78:81]
	v_mfma_f32_16x16x32_bf16 v[0:3], v[0:3], v[70:73], v[10:13]
	v_mfma_f32_16x16x32_bf16 v[8:11], v[4:7], v[58:61], v[42:45]
	v_mfma_f32_16x16x32_bf16 v[42:45], v[4:7], v[62:65], v[82:85]
	v_mfma_f32_16x16x32_bf16 v[82:85], v[4:7], v[66:69], v[86:89]
	v_mfma_f32_16x16x32_bf16 v[4:7], v[4:7], v[70:73], v[14:17]
	v_mfma_f32_16x16x32_bf16 v[12:15], v[50:53], v[58:61], v[46:49]
	v_mfma_f32_16x16x32_bf16 v[46:49], v[50:53], v[62:65], v[90:93]
	v_mfma_f32_16x16x32_bf16 v[86:89], v[50:53], v[66:69], v[94:97]
	v_mfma_f32_16x16x32_bf16 v[16:19], v[50:53], v[70:73], v[18:21]
	v_mfma_f32_16x16x32_bf16 v[26:29], v[54:57], v[58:61], v[26:29]
	v_mfma_f32_16x16x32_bf16 v[30:33], v[54:57], v[62:65], v[30:33]
	v_mfma_f32_16x16x32_bf16 v[34:37], v[54:57], v[66:69], v[34:37]
	v_mfma_f32_16x16x32_bf16 v[20:23], v[54:57], v[70:73], v[22:25]
	v_mfma_f32_16x16x32_bf16 v[38:41], v[98:101], v[114:117], v[38:41]
	v_mfma_f32_16x16x32_bf16 v[50:53], v[98:101], v[118:121], v[74:77]
	v_mfma_f32_16x16x32_bf16 v[54:57], v[98:101], v[122:125], v[78:81]
	v_mfma_f32_16x16x32_bf16 v[0:3], v[98:101], v[126:129], v[0:3]
	v_mfma_f32_16x16x32_bf16 v[8:11], v[102:105], v[114:117], v[8:11]
	v_mfma_f32_16x16x32_bf16 v[42:45], v[102:105], v[118:121], v[42:45]
	v_mfma_f32_16x16x32_bf16 v[58:61], v[102:105], v[122:125], v[82:85]
	v_mfma_f32_16x16x32_bf16 v[4:7], v[102:105], v[126:129], v[4:7]
	v_mfma_f32_16x16x32_bf16 v[12:15], v[106:109], v[114:117], v[12:15]
	v_mfma_f32_16x16x32_bf16 v[46:49], v[106:109], v[118:121], v[46:49]
	v_mfma_f32_16x16x32_bf16 v[62:65], v[106:109], v[122:125], v[86:89]
	v_mfma_f32_16x16x32_bf16 v[16:19], v[106:109], v[126:129], v[16:19]
	v_mfma_f32_16x16x32_bf16 v[24:27], v[110:113], v[114:117], v[26:29]
	v_mfma_f32_16x16x32_bf16 v[28:31], v[110:113], v[118:121], v[30:33]
	v_mfma_f32_16x16x32_bf16 v[32:35], v[110:113], v[122:125], v[34:37]
	v_mfma_f32_16x16x32_bf16 v[20:23], v[110:113], v[126:129], v[20:23]
	s_waitcnt vmcnt(6)
	s_waitcnt lgkmcnt(0)
	s_barrier
	s_add_i32 s0, 0, 0x18000
	v_add_u32_e32 v36, s0, v131
	v_add_u32_e32 v37, v36, v130
	ds_read_b128 v[66:69], v37
	ds_read_b128 v[70:73], v37 offset:2048
	ds_read_b128 v[74:77], v37 offset:4096
	ds_read_b128 v[78:81], v37 offset:6144
	v_add3_u32 v37, s0, v130, v132
	v_add_u32_e32 v36, v36, v133
	ds_read_b128 v[82:85], v37
	ds_read_b128 v[86:89], v37 offset:2048
	ds_read_b128 v[90:93], v37 offset:4096
	ds_read_b128 v[94:97], v37 offset:6144
	v_add3_u32 v37, s0, v133, v132
	ds_read_b128 v[98:101], v36
	ds_read_b128 v[102:105], v36 offset:2048
	ds_read_b128 v[106:109], v36 offset:4096
	ds_read_b128 v[110:113], v36 offset:6144
	ds_read_b128 v[114:117], v37
	ds_read_b128 v[118:121], v37 offset:2048
	ds_read_b128 v[122:125], v37 offset:4096
	ds_read_b128 v[126:129], v37 offset:6144
	s_waitcnt lgkmcnt(0)
	v_mfma_f32_16x16x32_bf16 v[36:39], v[66:69], v[82:85], v[38:41]
	v_mfma_f32_16x16x32_bf16 v[50:53], v[66:69], v[86:89], v[50:53]
	v_mfma_f32_16x16x32_bf16 v[54:57], v[66:69], v[90:93], v[54:57]
	v_mfma_f32_16x16x32_bf16 v[0:3], v[66:69], v[94:97], v[0:3]
	v_mfma_f32_16x16x32_bf16 v[8:11], v[70:73], v[82:85], v[8:11]
	v_mfma_f32_16x16x32_bf16 v[40:43], v[70:73], v[86:89], v[42:45]
	v_mfma_f32_16x16x32_bf16 v[58:61], v[70:73], v[90:93], v[58:61]
	v_mfma_f32_16x16x32_bf16 v[4:7], v[70:73], v[94:97], v[4:7]
	v_mfma_f32_16x16x32_bf16 v[12:15], v[74:77], v[82:85], v[12:15]
	v_mfma_f32_16x16x32_bf16 v[44:47], v[74:77], v[86:89], v[46:49]
	v_mfma_f32_16x16x32_bf16 v[62:65], v[74:77], v[90:93], v[62:65]
	v_mfma_f32_16x16x32_bf16 v[16:19], v[74:77], v[94:97], v[16:19]
	v_mfma_f32_16x16x32_bf16 v[24:27], v[78:81], v[82:85], v[24:27]
	v_mfma_f32_16x16x32_bf16 v[28:31], v[78:81], v[86:89], v[28:31]
	v_mfma_f32_16x16x32_bf16 v[32:35], v[78:81], v[90:93], v[32:35]
	v_mfma_f32_16x16x32_bf16 v[20:23], v[78:81], v[94:97], v[20:23]
	v_mfma_f32_16x16x32_bf16 v[36:39], v[98:101], v[114:117], v[36:39]
	v_mfma_f32_16x16x32_bf16 v[48:51], v[98:101], v[118:121], v[50:53]
	v_mfma_f32_16x16x32_bf16 v[52:55], v[98:101], v[122:125], v[54:57]
	v_mfma_f32_16x16x32_bf16 v[0:3], v[98:101], v[126:129], v[0:3]
	v_mfma_f32_16x16x32_bf16 v[8:11], v[102:105], v[114:117], v[8:11]
	v_mfma_f32_16x16x32_bf16 v[40:43], v[102:105], v[118:121], v[40:43]
	v_mfma_f32_16x16x32_bf16 v[56:59], v[102:105], v[122:125], v[58:61]
	v_mfma_f32_16x16x32_bf16 v[4:7], v[102:105], v[126:129], v[4:7]
	v_mfma_f32_16x16x32_bf16 v[12:15], v[106:109], v[114:117], v[12:15]
	v_mfma_f32_16x16x32_bf16 v[44:47], v[106:109], v[118:121], v[44:47]
	v_mfma_f32_16x16x32_bf16 v[60:63], v[106:109], v[122:125], v[62:65]
	v_mfma_f32_16x16x32_bf16 v[16:19], v[106:109], v[126:129], v[16:19]
	v_mfma_f32_16x16x32_bf16 v[24:27], v[110:113], v[114:117], v[24:27]
	v_mfma_f32_16x16x32_bf16 v[28:31], v[110:113], v[118:121], v[28:31]
	v_mfma_f32_16x16x32_bf16 v[32:35], v[110:113], v[122:125], v[32:35]
	v_mfma_f32_16x16x32_bf16 v[20:23], v[110:113], v[126:129], v[20:23]
	s_waitcnt vmcnt(0)
	s_waitcnt lgkmcnt(0)
	s_barrier
	ds_read_b128 v[64:67], v134
	ds_read_b128 v[68:71], v134 offset:2048
	ds_read_b128 v[72:75], v134 offset:4096
	ds_read_b128 v[76:79], v134 offset:6144
	ds_read_b128 v[80:83], v135 offset:32768
	ds_read_b128 v[84:87], v135 offset:34816
	ds_read_b128 v[88:91], v135 offset:36864
	ds_read_b128 v[92:95], v135 offset:38912
	ds_read_b128 v[96:99], v136
	ds_read_b128 v[100:103], v136 offset:2048
	ds_read_b128 v[104:107], v136 offset:4096
	ds_read_b128 v[108:111], v136 offset:6144
	ds_read_b128 v[112:115], v137 offset:32768
	ds_read_b128 v[116:119], v137 offset:34816
	ds_read_b128 v[120:123], v137 offset:36864
	ds_read_b128 v[124:127], v137 offset:38912
	s_waitcnt lgkmcnt(0)
	v_mfma_f32_16x16x32_bf16 v[36:39], v[64:67], v[80:83], v[36:39]
	v_mfma_f32_16x16x32_bf16 v[48:51], v[64:67], v[84:87], v[48:51]
	v_mfma_f32_16x16x32_bf16 v[52:55], v[64:67], v[88:91], v[52:55]
	v_mfma_f32_16x16x32_bf16 v[0:3], v[64:67], v[92:95], v[0:3]
	v_mfma_f32_16x16x32_bf16 v[8:11], v[68:71], v[80:83], v[8:11]
	v_mfma_f32_16x16x32_bf16 v[40:43], v[68:71], v[84:87], v[40:43]
	v_mfma_f32_16x16x32_bf16 v[56:59], v[68:71], v[88:91], v[56:59]
	v_mfma_f32_16x16x32_bf16 v[4:7], v[68:71], v[92:95], v[4:7]
	v_mfma_f32_16x16x32_bf16 v[12:15], v[72:75], v[80:83], v[12:15]
	v_mfma_f32_16x16x32_bf16 v[44:47], v[72:75], v[84:87], v[44:47]
	v_mfma_f32_16x16x32_bf16 v[60:63], v[72:75], v[88:91], v[60:63]
	v_mfma_f32_16x16x32_bf16 v[16:19], v[72:75], v[92:95], v[16:19]
	v_mfma_f32_16x16x32_bf16 v[24:27], v[76:79], v[80:83], v[24:27]
	v_mfma_f32_16x16x32_bf16 v[28:31], v[76:79], v[84:87], v[28:31]
	v_mfma_f32_16x16x32_bf16 v[32:35], v[76:79], v[88:91], v[32:35]
	v_mfma_f32_16x16x32_bf16 v[20:23], v[76:79], v[92:95], v[20:23]
	v_mfma_f32_16x16x32_bf16 v[36:39], v[96:99], v[112:115], v[36:39]
	v_mfma_f32_16x16x32_bf16 v[48:51], v[96:99], v[116:119], v[48:51]
	v_mfma_f32_16x16x32_bf16 v[52:55], v[96:99], v[120:123], v[52:55]
	v_mfma_f32_16x16x32_bf16 v[0:3], v[96:99], v[124:127], v[0:3]
	v_mfma_f32_16x16x32_bf16 v[8:11], v[100:103], v[112:115], v[8:11]
	v_mfma_f32_16x16x32_bf16 v[40:43], v[100:103], v[116:119], v[40:43]
	v_mfma_f32_16x16x32_bf16 v[56:59], v[100:103], v[120:123], v[56:59]
	v_mfma_f32_16x16x32_bf16 v[4:7], v[100:103], v[124:127], v[4:7]
	v_mfma_f32_16x16x32_bf16 v[12:15], v[104:107], v[112:115], v[12:15]
	v_mfma_f32_16x16x32_bf16 v[44:47], v[104:107], v[116:119], v[44:47]
	v_mfma_f32_16x16x32_bf16 v[60:63], v[104:107], v[120:123], v[60:63]
	v_mfma_f32_16x16x32_bf16 v[16:19], v[104:107], v[124:127], v[16:19]
	v_mfma_f32_16x16x32_bf16 v[24:27], v[108:111], v[112:115], v[24:27]
	v_mfma_f32_16x16x32_bf16 v[28:31], v[108:111], v[116:119], v[28:31]
	v_mfma_f32_16x16x32_bf16 v[32:35], v[108:111], v[120:123], v[32:35]
	v_mfma_f32_16x16x32_bf16 v[20:23], v[108:111], v[124:127], v[20:23]
	s_waitcnt vmcnt(0)
	v_mov_b32_e32 v64, v204
	s_lshl_b32 s2, s2, 2
	s_nop 1
	v_cvt_pk_bf16_f32 v16, v16, v17
	v_cvt_pk_bf16_f32 v17, v18, v19
	v_cvt_pk_bf16_f32 v18, v24, v25
	v_cvt_pk_bf16_f32 v24, v28, v29
	s_waitcnt lgkmcnt(0)
	s_barrier
	v_cvt_pk_bf16_f32 v20, v20, v21
	v_and_b32_e32 v28, 0x4f, v64
	v_cvt_pk_bf16_f32 v21, v22, v23
	s_or_b32 s8, s6, s2
	v_lshrrev_b32_e32 v22, 1, v64
	v_ashrrev_i32_e32 v29, 8, v64
	v_or_b32_e32 v28, s3, v28
	v_cvt_pk_bf16_f32 v25, v30, v31
	v_lshrrev_b32_e32 v23, 2, v64
	s_ashr_i32 s9, s8, 31
	v_and_b32_e32 v30, 64, v22
	v_add_u32_e32 v22, s7, v29
	v_lshlrev_b32_e32 v28, 6, v28
	s_and_b32 s0, s4, 0x100
	s_lshl_b64 s[2:3], s[8:9], 23
	v_and_or_b32 v29, v23, 12, v30
	v_ashrrev_i32_e32 v23, 31, v22
	v_and_b32_e32 v188, 0x33c0, v28
	v_cvt_pk_bf16_f32 v36, v36, v37
	v_cvt_pk_bf16_f32 v37, v38, v39
	v_cvt_pk_bf16_f32 v48, v48, v49
	v_cvt_pk_bf16_f32 v49, v50, v51
	v_mov_b32_e32 v51, v189
	v_cvt_pk_bf16_f32 v52, v52, v53
	v_cvt_pk_bf16_f32 v53, v54, v55
	v_mov_b32_e32 v55, v189
	s_add_u32 s2, s88, s2
	v_lshlrev_b32_e32 v38, 1, v29
	v_lshl_add_u64 v[28:29], v[188:189], 0, v[22:23]
	v_or_b32_e32 v50, 0x400, v188
	v_or_b32_e32 v54, 0x800, v188
	v_or_b32_e32 v188, 0xc00, v188
	v_cvt_pk_bf16_f32 v19, v26, v27
	v_cvt_pk_bf16_f32 v26, v32, v33
	s_addc_u32 s3, s89, s3
	v_lshlrev_b64 v[28:29], 9, v[28:29]
	v_lshl_add_u64 v[30:31], v[50:51], 0, v[22:23]
	v_lshl_add_u64 v[32:33], v[54:55], 0, v[22:23]
	v_lshl_add_u64 v[22:23], v[188:189], 0, v[22:23]
	v_lshl_add_u64 v[28:29], s[2:3], 0, v[28:29]
	v_lshlrev_b64 v[30:31], 9, v[30:31]
	v_lshlrev_b64 v[32:33], 9, v[32:33]
	v_lshlrev_b64 v[22:23], 9, v[22:23]
	v_mov_b32_e32 v39, v189
	s_add_i32 s5, s5, s96
	s_add_i32 s4, s4, s75
	v_lshl_add_u64 v[28:29], v[28:29], 0, s[0:1]
	v_lshl_add_u64 v[30:31], s[2:3], 0, v[30:31]
	v_lshl_add_u64 v[32:33], s[2:3], 0, v[32:33]
	v_lshl_add_u64 v[22:23], s[2:3], 0, v[22:23]
	v_cvt_pk_bf16_f32 v0, v0, v1
	v_cvt_pk_bf16_f32 v1, v2, v3
	v_cvt_pk_bf16_f32 v2, v8, v9
	v_cvt_pk_bf16_f32 v3, v10, v11
	s_cmpk_gt_i32 s5, 0x7ff
	v_lshl_add_u64 v[28:29], v[28:29], 0, v[38:39]
	v_lshl_add_u64 v[30:31], v[30:31], 0, s[0:1]
	v_lshl_add_u64 v[32:33], v[32:33], 0, s[0:1]
	v_lshl_add_u64 v[22:23], v[22:23], 0, s[0:1]
	v_cvt_pk_bf16_f32 v8, v40, v41
	v_cvt_pk_bf16_f32 v9, v42, v43
	v_cvt_pk_bf16_f32 v10, v56, v57
	v_cvt_pk_bf16_f32 v11, v58, v59
	v_cvt_pk_bf16_f32 v4, v4, v5
	v_cvt_pk_bf16_f32 v5, v6, v7
	v_cvt_pk_bf16_f32 v6, v12, v13
	v_cvt_pk_bf16_f32 v7, v14, v15
	v_cvt_pk_bf16_f32 v12, v44, v45
	v_cvt_pk_bf16_f32 v13, v46, v47
	v_cvt_pk_bf16_f32 v14, v60, v61
	v_cvt_pk_bf16_f32 v15, v62, v63
	v_cvt_pk_bf16_f32 v27, v34, v35
	v_lshl_add_u64 v[30:31], v[30:31], 0, v[38:39]
	v_lshl_add_u64 v[32:33], v[32:33], 0, v[38:39]
	v_lshl_add_u64 v[22:23], v[22:23], 0, v[38:39]
	v_and_b32_e32 v230, 16, v204
	v_lshrrev_b32_e32 v231, 1, v230
	v_add_u32_e32 v230, v230, v231
	v_mov_b32_e32 v231, v189
	v_lshl_add_u64 v[22:23], v[22:23], 0, v[230:231]
	v_lshl_add_u64 v[28:29], v[28:29], 0, v[230:231]
	v_lshl_add_u64 v[30:31], v[30:31], 0, v[230:231]
	v_lshl_add_u64 v[32:33], v[32:33], 0, v[230:231]
	v_mov_b64_e32 v[232:233], v[0:1]
	v_mov_b64_e32 v[234:235], v[4:5]
	s_nop 1
	v_permlane16_swap_b32 v232, v234
	v_permlane16_swap_b32 v233, v235
	global_store_dwordx4 v[22:23], v[232:235], off
	v_mov_b64_e32 v[236:237], v[16:17]
	v_mov_b64_e32 v[238:239], v[20:21]
	s_nop 1
	v_permlane16_swap_b32 v236, v238
	v_permlane16_swap_b32 v237, v239
	global_store_dwordx4 v[22:23], v[236:239], off offset:64
	v_mov_b64_e32 v[232:233], v[36:37]
	v_mov_b64_e32 v[234:235], v[2:3]
	s_nop 1
	v_permlane16_swap_b32 v232, v234
	v_permlane16_swap_b32 v233, v235
	global_store_dwordx4 v[28:29], v[232:235], off
	v_mov_b64_e32 v[236:237], v[6:7]
	v_mov_b64_e32 v[238:239], v[18:19]
	s_nop 1
	v_permlane16_swap_b32 v236, v238
	v_permlane16_swap_b32 v237, v239
	global_store_dwordx4 v[28:29], v[236:239], off offset:64
	v_mov_b64_e32 v[232:233], v[48:49]
	v_mov_b64_e32 v[234:235], v[8:9]
	s_nop 1
	v_permlane16_swap_b32 v232, v234
	v_permlane16_swap_b32 v233, v235
	global_store_dwordx4 v[30:31], v[232:235], off
	v_mov_b64_e32 v[236:237], v[12:13]
	v_mov_b64_e32 v[238:239], v[24:25]
	s_nop 1
	v_permlane16_swap_b32 v236, v238
	v_permlane16_swap_b32 v237, v239
	global_store_dwordx4 v[30:31], v[236:239], off offset:64
	v_mov_b64_e32 v[232:233], v[52:53]
	v_mov_b64_e32 v[234:235], v[10:11]
	s_nop 1
	v_permlane16_swap_b32 v232, v234
	v_permlane16_swap_b32 v233, v235
	global_store_dwordx4 v[32:33], v[232:235], off
	v_mov_b64_e32 v[236:237], v[14:15]
	v_mov_b64_e32 v[238:239], v[26:27]
	s_nop 1
	v_permlane16_swap_b32 v236, v238
	v_permlane16_swap_b32 v237, v239
	global_store_dwordx4 v[32:33], v[236:239], off offset:64
	s_cbranch_scc0 .LBB0_209
